# v61 + attention: full tiles run softmax interleaved with the neighbouring MFMA stages; K/V tile after next touched early with dword loads so the next fetch hits L2
# baseline (speedup 1.0000x reference)
.LBB0_335:
	s_and_b64 s[14:15], s[4:5], exec
	s_cselect_b32 s8, 1, 4
	s_cselect_b32 s0, s1, s0
	s_lshr_b32 s1, s12, s8
	s_and_b32 s1, s1, 3
	s_lshl_b32 s8, s1, 2
	v_readlane_b32 s12, v254, 44
	s_add_i32 s14, s8, s12
	s_lshl_b32 s12, s14, 6
	s_mov_b32 s8, s12
	s_and_b32 s16, s12, 0xffffff00
	v_writelane_b32 v255, s8, 6
	s_ashr_i32 s17, s16, 31
	s_lshl_b64 s[16:17], s[16:17], 1
	v_writelane_b32 v255, s9, 7
	v_readlane_b32 s8, v254, 45
	s_add_u32 s16, s8, s16
	v_readlane_b32 s8, v254, 46
	s_addc_u32 s17, s8, s17
	v_lshl_add_u64 v[188:189], s[70:71], 0, v[168:169]
	v_mov_b64_e32 v[0:1], s[16:17]
	v_mad_u64_u32 v[0:1], s[16:17], v188, s33, v[0:1]
	v_mov_b32_e32 v2, v1
	v_mad_u64_u32 v[2:3], s[16:17], v189, s33, v[2:3]
	v_mov_b32_e32 v1, v2
	v_lshl_add_u64 v[0:1], v[0:1], 0, v[176:177]
	s_mov_b64 s[16:17], 0x18000
	s_mov_b32 s8, 0x18000
	global_load_dwordx4 v[128:131], v[0:1], off
	global_load_dwordx4 v[132:135], v[0:1], off offset:32
	global_load_dwordx4 v[136:139], v[0:1], off offset:256
	global_load_dwordx4 v[140:143], v[0:1], off offset:288
	v_lshl_add_u64 v[2:3], v[0:1], 0, s[16:17]
	v_add_co_u32_e32 v0, vcc, s8, v0
	s_lshl_b32 s8, s11, 1
	s_sub_i32 s11, 2, s8
	s_sub_i32 s8, 33, s8
	s_max_i32 s16, s11, 0
	s_min_u32 s8, s8, 5
	s_sub_i32 s8, s8, s16
	s_add_i32 s8, s8, 5
	s_and_b64 s[4:5], s[4:5], exec
	s_cselect_b32 s11, 4, s8
	s_add_u32 s6, s6, 0x10000
	v_readlane_b32 s72, v254, 16
	s_addc_u32 s7, s7, 0
	s_ashr_i32 s15, s14, 31
	v_readlane_b32 s82, v254, 26
	v_readlane_b32 s83, v254, 27
	s_lshl_b32 s17, s1, 5
	s_lshl_b32 s4, s1, 6
	s_lshl_b64 s[14:15], s[14:15], 2
	s_mov_b64 s[70:71], s[82:83]
	s_add_u32 s14, s70, s14
	v_addc_co_u32_e32 v1, vcc, 0, v1, vcc
	s_addc_u32 s15, s71, s15
	global_load_dwordx4 v[144:147], v[2:3], off offset:32
	global_load_dwordx4 v[148:151], v[2:3], off offset:256
	global_load_dwordx4 v[152:155], v[0:1], off
	global_load_dwordx4 v[156:159], v[2:3], off offset:288
	global_load_dword v64, v173, s[14:15]
	v_lshl_add_u64 v[0:1], s[6:7], 0, v[170:171]
	v_mad_u64_u32 v[2:3], s[14:15], v0, s33, v[178:179]
	v_mov_b32_e32 v0, v3
	v_mad_u64_u32 v[0:1], s[14:15], v1, s33, v[0:1]
	v_mov_b32_e32 v3, v0
	s_lshl_b32 s8, s1, 7
	s_mov_b32 s5, s9
	v_lshl_add_u64 v[0:1], v[2:3], 0, s[8:9]
	v_lshl_add_u64 v[2:3], v[2:3], 0, v[172:173]
	v_lshl_add_u64 v[0:1], v[0:1], 0, v[182:183]
	v_lshl_add_u64 v[2:3], v[2:3], 0, s[4:5]
	v_lshl_add_u64 v[2:3], v[2:3], 0, v[186:187]
	global_load_dwordx4 v[160:163], v[0:1], off offset:2560
	global_load_dwordx4 v[164:167], v[2:3], off offset:2048
	v_add_co_u32_e32 v68, vcc, 0x30000, v0
	v_addc_co_u32_e32 v69, vcc, 0, v1, vcc
	v_add_co_u32_e32 v70, vcc, 0x30000, v2
	v_addc_co_u32_e32 v71, vcc, 0, v3, vcc
	global_load_dword v249, v[68:69], off offset:2560
	global_load_dword v250, v[70:71], off offset:2048
	s_ashr_i32 s1, s0, 31
	s_lshl_b64 s[0:1], s[0:1], 11
	s_or_b32 s0, s0, s13
	s_add_u32 s13, s0, 0xffffff80
	s_addc_u32 s14, s1, -1
	s_lshl_b32 s16, s16, 6
	v_readlane_b32 s0, v255, 4
	s_add_i32 s15, s0, s16
	v_readlane_b32 s0, v254, 47
	v_mov_b32_e32 v48, v173
	v_mov_b32_e32 v49, v173
	v_readlane_b32 s1, v254, 48
	v_mov_b32_e32 v50, v173
	v_mov_b32_e32 v51, v173
	v_mov_b32_e32 v52, v173
	v_mov_b32_e32 v53, v173
	v_mov_b32_e32 v54, v173
	v_mov_b32_e32 v55, v173
	v_mov_b32_e32 v56, v173
	v_mov_b32_e32 v57, v173
	v_mov_b32_e32 v58, v173
	v_mov_b32_e32 v59, v173
	v_mov_b32_e32 v60, v173
	v_mov_b32_e32 v61, v173
	v_mov_b32_e32 v62, v173
	v_mov_b32_e32 v63, v173
	v_mov_b64_e32 v[16:17], v[48:49]
	v_mov_b64_e32 v[32:33], v[48:49]
	v_mov_b64_e32 v[0:1], v[48:49]
	s_mov_b32 s12, 0
	v_mov_b64_e32 v[18:19], v[50:51]
	v_mov_b64_e32 v[20:21], v[52:53]
	v_mov_b64_e32 v[22:23], v[54:55]
	v_mov_b64_e32 v[24:25], v[56:57]
	v_mov_b64_e32 v[26:27], v[58:59]
	v_mov_b64_e32 v[28:29], v[60:61]
	v_mov_b64_e32 v[30:31], v[62:63]
	v_mov_b64_e32 v[34:35], v[50:51]
	v_mov_b64_e32 v[36:37], v[52:53]
	v_mov_b64_e32 v[38:39], v[54:55]
	v_mov_b64_e32 v[40:41], v[56:57]
	v_mov_b64_e32 v[42:43], v[58:59]
	v_mov_b64_e32 v[44:45], v[60:61]
	v_mov_b64_e32 v[46:47], v[62:63]
	v_mov_b64_e32 v[2:3], v[50:51]
	v_mov_b64_e32 v[4:5], v[52:53]
	v_mov_b64_e32 v[6:7], v[54:55]
	v_mov_b64_e32 v[8:9], v[56:57]
	v_mov_b64_e32 v[10:11], v[58:59]
	v_mov_b64_e32 v[12:13], v[60:61]
	v_mov_b64_e32 v[14:15], v[62:63]
	s_lshl_b32 s8, s17, 1
	s_lshl_b32 s4, s4, 1
	s_addk_i32 s16, 0xff40
	s_mov_b32 s72, 0
	v_readlane_b32 s73, v254, 17
	v_readlane_b32 s74, v254, 18
	v_readlane_b32 s75, v254, 19
	v_readlane_b32 s76, v254, 20
	v_readlane_b32 s77, v254, 21
	v_readlane_b32 s78, v254, 22
	v_readlane_b32 s79, v254, 23
	v_readlane_b32 s80, v254, 24
	v_readlane_b32 s81, v254, 25
	s_waitcnt vmcnt(4)
	v_mul_f32_e32 v64, 0x3fb8aa3b, v64
	v_exp_f32_e32 v64, v64
	v_readlane_b32 s84, v254, 28
	v_readlane_b32 s85, v254, 29
	v_readlane_b32 s86, v254, 30
	v_cndmask_b32_e64 v190, 0, v64, s[0:1]
	v_mov_b32_e32 v191, v190
	v_readlane_b32 s87, v254, 31
.LBB0_336:
	s_add_i32 s17, s72, 1
	s_cmp_ge_u32 s17, s11
	s_barrier
	s_waitcnt vmcnt(2)
	ds_write_b128 v193, v[164:167]
	ds_write_b128 v193, v[160:163] offset:9216
	s_waitcnt lgkmcnt(0)
	s_barrier
	s_cbranch_scc1 .LBB0_342
	s_cmp_gt_u32 s72, 2
	s_mov_b64 s[70:71], -1
	s_cbranch_scc0 .LBB0_339
	s_add_i32 s0, s16, s12
	s_ashr_i32 s1, s0, 31
	s_add_u32 s0, s13, s0
	s_addc_u32 s1, s14, s1
	s_mov_b64 s[70:71], 0

.LBB0_341:
	v_lshl_add_u64 v[64:65], s[0:1], 0, v[170:171]
	v_mov_b64_e32 v[66:67], s[2:3]
	v_mad_u64_u32 v[66:67], s[0:1], v64, s33, v[66:67]
	v_mov_b32_e32 v64, v67
	v_mad_u64_u32 v[64:65], s[0:1], v65, s33, v[64:65]
	v_mov_b32_e32 v67, v64
	v_lshl_add_u64 v[64:65], v[66:67], 0, v[172:173]
	v_lshl_add_u64 v[64:65], v[64:65], 0, s[8:9]
	v_mov_b32_e32 v185, v173
	s_mov_b32 s5, s9
	v_lshl_add_u64 v[64:65], v[64:65], 0, v[184:185]
	v_lshl_add_u64 v[66:67], v[66:67], 0, s[4:5]
	v_mov_b32_e32 v181, v173
	v_lshl_add_u64 v[66:67], v[66:67], 0, v[180:181]
	global_load_dwordx4 v[164:167], v[64:65], off offset:2048
	global_load_dwordx4 v[160:163], v[66:67], off offset:2560
	s_cmp_lt_u32 s72, 2
	s_cbranch_scc1 .Lapf_far
	s_cmp_lt_u32 s72, 3
	s_cbranch_scc1 .Lapf_near
	s_add_i32 s0, s72, 2
	s_cmp_lt_u32 s0, s11
	s_cbranch_scc0 .Lapf_near
.Lapf_far:
	v_add_co_u32_e32 v64, vcc, 0x30000, v64
	v_addc_co_u32_e32 v65, vcc, 0, v65, vcc
	v_add_co_u32_e32 v66, vcc, 0x30000, v66
	v_addc_co_u32_e32 v67, vcc, 0, v67, vcc
.Lapf_near:
	global_load_dword v249, v[64:65], off offset:2048
	global_load_dword v250, v[66:67], off offset:2560
.LBB0_342:
	s_add_i32 s0, s15, s12
	s_cmp_gt_u32 s72, 3
	s_cselect_b32 s5, s0, 0
	s_add_i32 s0, s5, 0xffffff40
	s_cmp_lt_u32 s0, 0xfffffe81
	s_cbranch_scc1 .LBB0_350
	s_cmpk_eq_i32 s5, 0x80
	s_cbranch_scc1 .Lat2_orig
	s_cmpk_eq_i32 s5, 0xff80
	s_cbranch_scc0 .Lat2_full
.Lat2_orig:
	ds_read_b128 v[64:67], v194
	ds_read_b128 v[68:71], v194 offset:32
	s_cmpk_lt_i32 s5, 0x80
	s_waitcnt lgkmcnt(1)
	v_mfma_f32_32x32x16_bf16 v[112:127], v[64:67], v[128:131], 0
	ds_read_b128 v[202:205], v194 offset:4640
	v_mfma_f32_32x32x16_bf16 v[80:95], v[64:67], v[152:155], 0
	ds_read_b128 v[64:67], v194 offset:64
	s_waitcnt lgkmcnt(2)
	v_mfma_f32_32x32x16_bf16 v[112:127], v[68:71], v[132:135], v[112:127]
	v_mfma_f32_32x32x16_bf16 v[80:95], v[68:71], v[144:147], v[80:95]
	s_waitcnt lgkmcnt(0)
	v_mfma_f32_32x32x16_bf16 v[112:127], v[64:67], v[136:139], v[112:127]
	v_mfma_f32_32x32x16_bf16 v[80:95], v[64:67], v[148:151], v[80:95]
	ds_read_b128 v[64:67], v194 offset:96
	s_waitcnt lgkmcnt(0)
	v_mfma_f32_32x32x16_bf16 v[112:127], v[64:67], v[140:143], v[112:127]
	v_mfma_f32_32x32x16_bf16 v[80:95], v[64:67], v[156:159], v[80:95]
	ds_read_b128 v[64:67], v194 offset:4608
	s_waitcnt lgkmcnt(0)
	v_mfma_f32_32x32x16_bf16 v[96:111], v[64:67], v[128:131], 0
	v_mfma_f32_32x32x16_bf16 v[64:79], v[64:67], v[152:155], 0
	v_mfma_f32_32x32x16_bf16 v[96:111], v[202:205], v[132:135], v[96:111]
	v_mfma_f32_32x32x16_bf16 v[64:79], v[202:205], v[144:147], v[64:79]
	ds_read_b128 v[202:205], v194 offset:4672
	s_waitcnt lgkmcnt(0)
	v_mfma_f32_32x32x16_bf16 v[96:111], v[202:205], v[136:139], v[96:111]
	v_mfma_f32_32x32x16_bf16 v[64:79], v[202:205], v[148:151], v[64:79]
	ds_read_b128 v[202:205], v194 offset:4704
	s_waitcnt lgkmcnt(0)
	v_mfma_f32_32x32x16_bf16 v[96:111], v[202:205], v[140:143], v[96:111]
	v_mfma_f32_32x32x16_bf16 v[64:79], v[202:205], v[156:159], v[64:79]
	s_cbranch_scc1 .LBB0_345
	s_cmpk_eq_i32 s5, 0x80
	s_cselect_b64 s[0:1], -1, 0
	s_cbranch_execz .LBB0_346
	s_branch .LBB0_347

.LBB0_349:
	v_exp_f32_e32 v198, v112
	v_exp_f32_e32 v199, v80
	v_exp_f32_e32 v202, v113
	v_exp_f32_e32 v203, v81
	v_exp_f32_e32 v204, v114
	v_exp_f32_e32 v205, v82
	v_exp_f32_e32 v206, v115
	v_exp_f32_e32 v207, v83
	v_exp_f32_e32 v208, v116
	v_exp_f32_e32 v209, v84
	v_exp_f32_e32 v211, v85
	v_pk_add_f32 v[84:85], v[198:199], 0 op_sel_hi:[1,0]
	v_exp_f32_e32 v210, v117
	v_pk_add_f32 v[84:85], v[202:203], v[84:85]
	v_exp_f32_e32 v212, v118
	v_exp_f32_e32 v213, v86
	v_pk_add_f32 v[84:85], v[204:205], v[84:85]
	v_exp_f32_e32 v214, v119
	v_exp_f32_e32 v215, v87
	v_pk_add_f32 v[84:85], v[206:207], v[84:85]
	v_exp_f32_e32 v120, v120
	v_exp_f32_e32 v216, v121
	v_exp_f32_e32 v121, v88
	v_pk_add_f32 v[84:85], v[208:209], v[84:85]
	v_exp_f32_e32 v217, v89
	v_pk_add_f32 v[84:85], v[210:211], v[84:85]
	v_exp_f32_e32 v122, v122
	v_exp_f32_e32 v218, v123
	v_exp_f32_e32 v123, v90
	v_pk_add_f32 v[84:85], v[212:213], v[84:85]
	v_exp_f32_e32 v219, v91
	v_pk_add_f32 v[84:85], v[214:215], v[84:85]
	v_exp_f32_e32 v124, v124
	v_exp_f32_e32 v220, v125
	v_pk_add_f32 v[84:85], v[120:121], v[84:85]
	v_exp_f32_e32 v125, v92
	v_pk_add_f32 v[84:85], v[216:217], v[84:85]
	v_exp_f32_e32 v221, v93
	v_exp_f32_e32 v126, v126
	v_exp_f32_e32 v222, v127
	v_pk_add_f32 v[88:89], v[122:123], v[84:85]
	v_exp_f32_e32 v127, v94
	v_exp_f32_e32 v223, v95
	v_exp_f32_e32 v225, v64
	v_exp_f32_e32 v227, v65
	v_pk_add_f32 v[64:65], v[218:219], v[88:89]
	v_exp_f32_e32 v224, v96
	v_pk_add_f32 v[64:65], v[124:125], v[64:65]
	v_exp_f32_e32 v226, v97
	v_pk_add_f32 v[64:65], v[220:221], v[64:65]
	v_exp_f32_e32 v228, v98
	v_exp_f32_e32 v229, v66
	v_pk_add_f32 v[64:65], v[126:127], v[64:65]
	v_exp_f32_e32 v230, v99
	v_exp_f32_e32 v231, v67
	v_pk_add_f32 v[64:65], v[222:223], v[64:65]
	v_exp_f32_e32 v232, v100
	v_exp_f32_e32 v233, v68
	v_pk_add_f32 v[64:65], v[224:225], v[64:65]
	v_exp_f32_e32 v234, v101
	v_exp_f32_e32 v235, v69
	v_pk_add_f32 v[64:65], v[226:227], v[64:65]
	v_exp_f32_e32 v236, v102
	v_pk_add_f32 v[64:65], v[228:229], v[64:65]
	v_exp_f32_e32 v237, v70
	v_exp_f32_e32 v238, v103
	v_pk_add_f32 v[64:65], v[230:231], v[64:65]
	v_exp_f32_e32 v239, v71
	v_exp_f32_e32 v104, v104
	v_exp_f32_e32 v240, v105
	v_pk_add_f32 v[64:65], v[232:233], v[64:65]
	v_exp_f32_e32 v105, v72
	v_pk_add_f32 v[68:69], v[234:235], v[64:65]
	v_exp_f32_e32 v241, v73
	v_exp_f32_e32 v106, v106
	v_exp_f32_e32 v242, v107
	v_exp_f32_e32 v107, v74
	v_pk_add_f32 v[68:69], v[236:237], v[68:69]
	v_exp_f32_e32 v243, v75
	v_pk_add_f32 v[68:69], v[238:239], v[68:69]
	v_exp_f32_e32 v108, v108
	v_exp_f32_e32 v244, v109
	v_exp_f32_e32 v109, v76
	v_pk_add_f32 v[68:69], v[104:105], v[68:69]
	v_exp_f32_e32 v245, v77
	v_pk_add_f32 v[68:69], v[240:241], v[68:69]
	v_exp_f32_e32 v110, v110
	v_exp_f32_e32 v246, v111
	v_exp_f32_e32 v111, v78
	v_pk_add_f32 v[68:69], v[106:107], v[68:69]
	v_exp_f32_e32 v247, v79
	v_pk_add_f32 v[68:69], v[242:243], v[68:69]
	v_cvt_pk_bf16_f32 v116, v198, v202
	v_cvt_pk_bf16_f32 v117, v204, v206
	v_cvt_pk_bf16_f32 v118, v208, v210
	v_cvt_pk_bf16_f32 v119, v212, v214
	v_cvt_pk_bf16_f32 v112, v120, v216
	s_nop 0
	v_pk_add_f32 v[68:69], v[108:109], v[68:69]
	v_cvt_pk_bf16_f32 v113, v122, v218
	v_cvt_pk_bf16_f32 v114, v124, v220
	v_cvt_pk_bf16_f32 v115, v126, v222
	v_cvt_pk_bf16_f32 v100, v224, v226
	v_cvt_pk_bf16_f32 v101, v228, v230
	s_nop 0
	v_pk_add_f32 v[68:69], v[244:245], v[68:69]
	v_cvt_pk_bf16_f32 v102, v232, v234
	v_cvt_pk_bf16_f32 v103, v236, v238
	v_cvt_pk_bf16_f32 v96, v104, v240
	v_cvt_pk_bf16_f32 v97, v106, v242
	v_cvt_pk_bf16_f32 v98, v108, v244
	s_nop 0
	v_pk_add_f32 v[68:69], v[110:111], v[68:69]
	v_cvt_pk_bf16_f32 v99, v110, v246
	v_cvt_pk_bf16_f32 v80, v199, v203
	v_cvt_pk_bf16_f32 v81, v205, v207
	v_cvt_pk_bf16_f32 v82, v209, v211
	v_cvt_pk_bf16_f32 v83, v213, v215
	s_nop 0
	v_pk_add_f32 v[72:73], v[246:247], v[68:69]
	v_cvt_pk_bf16_f32 v84, v121, v217
	v_cvt_pk_bf16_f32 v85, v123, v219
	v_cvt_pk_bf16_f32 v86, v125, v221
	v_cvt_pk_bf16_f32 v87, v127, v223
	v_cvt_pk_bf16_f32 v64, v225, v227
	s_nop 0
	v_pk_add_f32 v[190:191], v[190:191], v[72:73]
	v_cvt_pk_bf16_f32 v65, v229, v231
	v_cvt_pk_bf16_f32 v66, v233, v235
	v_cvt_pk_bf16_f32 v67, v237, v239
	v_cvt_pk_bf16_f32 v68, v105, v241
	v_cvt_pk_bf16_f32 v69, v107, v243
	v_cvt_pk_bf16_f32 v70, v109, v245
	v_cvt_pk_bf16_f32 v71, v111, v247
	ds_read_b64_tr_b16 v[206:207], v195 offset:9216
	ds_read_b64_tr_b16 v[208:209], v195 offset:10368
	ds_read_b64_tr_b16 v[210:211], v195 offset:9280
	ds_read_b64_tr_b16 v[212:213], v195 offset:10432
	ds_read_b64_tr_b16 v[214:215], v195 offset:11520
	ds_read_b64_tr_b16 v[216:217], v195 offset:12672
	ds_read_b64_tr_b16 v[218:219], v195 offset:11584
	ds_read_b64_tr_b16 v[220:221], v195 offset:12736
	ds_read_b64_tr_b16 v[222:223], v195 offset:13824
	ds_read_b64_tr_b16 v[224:225], v195 offset:14976
	ds_read_b64_tr_b16 v[226:227], v195 offset:13888
	ds_read_b64_tr_b16 v[228:229], v195 offset:15040
	s_waitcnt lgkmcnt(10)
	v_mfma_f32_32x32x16_bf16 v[48:63], v[206:209], v[116:119], v[48:63]
	v_mfma_f32_32x32x16_bf16 v[16:31], v[206:209], v[80:83], v[16:31]
	ds_read_b64_tr_b16 v[230:231], v195 offset:16128
	ds_read_b64_tr_b16 v[232:233], v195 offset:17280
	s_waitcnt lgkmcnt(10)
	v_mfma_f32_32x32x16_bf16 v[32:47], v[210:213], v[116:119], v[32:47]
	v_mfma_f32_32x32x16_bf16 v[0:15], v[210:213], v[80:83], v[0:15]
	ds_read_b64_tr_b16 v[234:235], v195 offset:16192
	ds_read_b64_tr_b16 v[236:237], v195 offset:17344
	s_waitcnt lgkmcnt(10)
	v_mfma_f32_32x32x16_bf16 v[48:63], v[214:217], v[112:115], v[48:63]
	v_mfma_f32_32x32x16_bf16 v[16:31], v[214:217], v[84:87], v[16:31]
	s_waitcnt lgkmcnt(8)
	v_mfma_f32_32x32x16_bf16 v[32:47], v[218:221], v[112:115], v[32:47]
	v_mfma_f32_32x32x16_bf16 v[0:15], v[218:221], v[84:87], v[0:15]
	s_waitcnt lgkmcnt(6)
	v_mfma_f32_32x32x16_bf16 v[48:63], v[222:225], v[100:103], v[48:63]
	v_mfma_f32_32x32x16_bf16 v[16:31], v[222:225], v[64:67], v[16:31]
	s_waitcnt lgkmcnt(4)
	v_mfma_f32_32x32x16_bf16 v[0:15], v[226:229], v[64:67], v[0:15]
	v_mfma_f32_32x32x16_bf16 v[32:47], v[226:229], v[100:103], v[32:47]
	s_waitcnt lgkmcnt(2)
	v_mfma_f32_32x32x16_bf16 v[48:63], v[230:233], v[96:99], v[48:63]
	v_mfma_f32_32x32x16_bf16 v[16:31], v[230:233], v[68:71], v[16:31]
	s_waitcnt lgkmcnt(0)
	v_mfma_f32_32x32x16_bf16 v[32:47], v[234:237], v[96:99], v[32:47]
	v_mfma_f32_32x32x16_bf16 v[0:15], v[234:237], v[68:71], v[0:15]
	s_branch .LBB0_350
.Lat2_full:
	ds_read_b128 v[96:99], v194
	ds_read_b128 v[100:103], v194 offset:32
	ds_read_b128 v[202:205], v194 offset:4608
	s_waitcnt lgkmcnt(2)
	v_mfma_f32_32x32x16_bf16 v[112:127], v[96:99], v[128:131], 0
	v_mfma_f32_32x32x16_bf16 v[80:95], v[96:99], v[152:155], 0
	ds_read_b128 v[96:99], v194 offset:64
	s_waitcnt lgkmcnt(2)
	v_mfma_f32_32x32x16_bf16 v[112:127], v[100:103], v[132:135], v[112:127]
	v_mfma_f32_32x32x16_bf16 v[80:95], v[100:103], v[144:147], v[80:95]
	ds_read_b128 v[100:103], v194 offset:96
	s_waitcnt lgkmcnt(1)
	v_mfma_f32_32x32x16_bf16 v[112:127], v[96:99], v[136:139], v[112:127]
	v_mfma_f32_32x32x16_bf16 v[80:95], v[96:99], v[148:151], v[80:95]
	ds_read_b128 v[240:243], v194 offset:4640
	s_waitcnt lgkmcnt(1)
	v_mfma_f32_32x32x16_bf16 v[112:127], v[100:103], v[140:143], v[112:127]
	v_mfma_f32_32x32x16_bf16 v[80:95], v[100:103], v[156:159], v[80:95]
	v_mfma_f32_32x32x16_bf16 v[96:111], v[202:205], v[128:131], 0
	v_mfma_f32_32x32x16_bf16 v[64:79], v[202:205], v[152:155], 0
	ds_read_b128 v[202:205], v194 offset:4672
	s_nop 7
	v_exp_f32_e32 v112, v112
	v_exp_f32_e32 v113, v113
	v_exp_f32_e32 v114, v114
	v_exp_f32_e32 v115, v115
	v_exp_f32_e32 v116, v116
	v_exp_f32_e32 v117, v117
	v_exp_f32_e32 v118, v118
	v_exp_f32_e32 v119, v119
	v_exp_f32_e32 v120, v120
	v_exp_f32_e32 v121, v121
	v_exp_f32_e32 v122, v122
	v_exp_f32_e32 v123, v123
	v_exp_f32_e32 v124, v124
	v_exp_f32_e32 v125, v125
	v_exp_f32_e32 v126, v126
	v_exp_f32_e32 v127, v127
	s_waitcnt lgkmcnt(1)
	v_mfma_f32_32x32x16_bf16 v[96:111], v[240:243], v[132:135], v[96:111]
	v_mfma_f32_32x32x16_bf16 v[64:79], v[240:243], v[144:147], v[64:79]
	ds_read_b128 v[240:243], v194 offset:4704
	v_exp_f32_e32 v80, v80
	v_pk_add_f32 v[238:239], v[112:113], v[114:115]
	v_exp_f32_e32 v81, v81
	v_pk_add_f32 v[238:239], v[238:239], v[116:117]
	v_exp_f32_e32 v82, v82
	v_pk_add_f32 v[238:239], v[238:239], v[118:119]
	v_exp_f32_e32 v83, v83
	v_pk_add_f32 v[238:239], v[238:239], v[120:121]
	v_exp_f32_e32 v84, v84
	v_pk_add_f32 v[238:239], v[238:239], v[122:123]
	v_exp_f32_e32 v85, v85
	v_pk_add_f32 v[238:239], v[238:239], v[124:125]
	v_exp_f32_e32 v86, v86
	v_pk_add_f32 v[238:239], v[238:239], v[126:127]
	v_exp_f32_e32 v87, v87
	v_cvt_pk_bf16_f32 v112, v112, v113
	s_waitcnt lgkmcnt(1)
	v_mfma_f32_32x32x16_bf16 v[96:111], v[202:205], v[136:139], v[96:111]
	v_mfma_f32_32x32x16_bf16 v[64:79], v[202:205], v[148:151], v[64:79]
	v_exp_f32_e32 v88, v88
	v_cvt_pk_bf16_f32 v113, v114, v115
	v_exp_f32_e32 v89, v89
	v_cvt_pk_bf16_f32 v114, v116, v117
	v_exp_f32_e32 v90, v90
	v_cvt_pk_bf16_f32 v115, v118, v119
	v_exp_f32_e32 v91, v91
	v_cvt_pk_bf16_f32 v116, v120, v121
	v_exp_f32_e32 v92, v92
	v_cvt_pk_bf16_f32 v117, v122, v123
	v_exp_f32_e32 v93, v93
	v_cvt_pk_bf16_f32 v118, v124, v125
	v_exp_f32_e32 v94, v94
	v_cvt_pk_bf16_f32 v119, v126, v127
	v_exp_f32_e32 v95, v95
	s_nop 0
	v_pk_add_f32 v[244:245], v[80:81], v[82:83]
	s_waitcnt lgkmcnt(0)
	v_mfma_f32_32x32x16_bf16 v[96:111], v[240:243], v[140:143], v[96:111]
	v_mfma_f32_32x32x16_bf16 v[64:79], v[240:243], v[156:159], v[64:79]
	ds_read_b64_tr_b16 v[206:207], v195 offset:9216
	ds_read_b64_tr_b16 v[208:209], v195 offset:10368
	ds_read_b64_tr_b16 v[210:211], v195 offset:9280
	ds_read_b64_tr_b16 v[212:213], v195 offset:10432
	v_pk_add_f32 v[244:245], v[244:245], v[84:85]
	v_cvt_pk_bf16_f32 v80, v80, v81
	v_pk_add_f32 v[244:245], v[244:245], v[86:87]
	v_cvt_pk_bf16_f32 v81, v82, v83
	ds_read_b64_tr_b16 v[214:215], v195 offset:11520
	ds_read_b64_tr_b16 v[216:217], v195 offset:12672
	v_pk_add_f32 v[244:245], v[244:245], v[88:89]
	v_cvt_pk_bf16_f32 v82, v84, v85
	v_pk_add_f32 v[244:245], v[244:245], v[90:91]
	v_cvt_pk_bf16_f32 v83, v86, v87
	ds_read_b64_tr_b16 v[218:219], v195 offset:11584
	ds_read_b64_tr_b16 v[220:221], v195 offset:12736
	v_pk_add_f32 v[244:245], v[244:245], v[92:93]
	v_cvt_pk_bf16_f32 v84, v88, v89
	v_pk_add_f32 v[244:245], v[244:245], v[94:95]
	v_cvt_pk_bf16_f32 v85, v90, v91
	v_cvt_pk_bf16_f32 v86, v92, v93
	v_cvt_pk_bf16_f32 v87, v94, v95
	s_waitcnt lgkmcnt(6)
	v_mfma_f32_32x32x16_bf16 v[48:63], v[206:209], v[112:115], v[48:63]
	v_mfma_f32_32x32x16_bf16 v[16:31], v[206:209], v[80:83], v[16:31]
	ds_read_b64_tr_b16 v[222:223], v195 offset:13824
	ds_read_b64_tr_b16 v[224:225], v195 offset:14976
	v_exp_f32_e32 v96, v96
	v_exp_f32_e32 v97, v97
	v_exp_f32_e32 v98, v98
	v_exp_f32_e32 v99, v99
	v_exp_f32_e32 v100, v100
	v_exp_f32_e32 v101, v101
	v_exp_f32_e32 v102, v102
	v_exp_f32_e32 v103, v103
	v_exp_f32_e32 v104, v104
	v_exp_f32_e32 v105, v105
	v_exp_f32_e32 v106, v106
	v_exp_f32_e32 v107, v107
	v_exp_f32_e32 v108, v108
	v_exp_f32_e32 v109, v109
	v_exp_f32_e32 v110, v110
	v_exp_f32_e32 v111, v111
	s_waitcnt lgkmcnt(6)
	v_mfma_f32_32x32x16_bf16 v[32:47], v[210:213], v[112:115], v[32:47]
	v_mfma_f32_32x32x16_bf16 v[0:15], v[210:213], v[80:83], v[0:15]
	ds_read_b64_tr_b16 v[226:227], v195 offset:13888
	ds_read_b64_tr_b16 v[228:229], v195 offset:15040
	v_exp_f32_e32 v64, v64
	v_pk_add_f32 v[238:239], v[238:239], v[96:97]
	v_exp_f32_e32 v65, v65
	v_pk_add_f32 v[238:239], v[238:239], v[98:99]
	v_exp_f32_e32 v66, v66
	v_pk_add_f32 v[238:239], v[238:239], v[100:101]
	v_exp_f32_e32 v67, v67
	v_pk_add_f32 v[238:239], v[238:239], v[102:103]
	v_exp_f32_e32 v68, v68
	v_pk_add_f32 v[238:239], v[238:239], v[104:105]
	v_exp_f32_e32 v69, v69
	v_pk_add_f32 v[238:239], v[238:239], v[106:107]
	v_exp_f32_e32 v70, v70
	v_pk_add_f32 v[238:239], v[238:239], v[108:109]
	v_exp_f32_e32 v71, v71
	v_pk_add_f32 v[238:239], v[238:239], v[110:111]
	s_waitcnt lgkmcnt(6)
	v_mfma_f32_32x32x16_bf16 v[48:63], v[214:217], v[116:119], v[48:63]
	v_mfma_f32_32x32x16_bf16 v[16:31], v[214:217], v[84:87], v[16:31]
	ds_read_b64_tr_b16 v[230:231], v195 offset:16128
	ds_read_b64_tr_b16 v[232:233], v195 offset:17280
	v_exp_f32_e32 v72, v72
	v_cvt_pk_bf16_f32 v96, v96, v97
	v_exp_f32_e32 v73, v73
	v_cvt_pk_bf16_f32 v97, v98, v99
	v_exp_f32_e32 v74, v74
	v_cvt_pk_bf16_f32 v98, v100, v101
	v_exp_f32_e32 v75, v75
	v_cvt_pk_bf16_f32 v99, v102, v103
	v_exp_f32_e32 v76, v76
	v_cvt_pk_bf16_f32 v100, v104, v105
	v_exp_f32_e32 v77, v77
	v_cvt_pk_bf16_f32 v101, v106, v107
	v_exp_f32_e32 v78, v78
	v_cvt_pk_bf16_f32 v102, v108, v109
	v_exp_f32_e32 v79, v79
	v_cvt_pk_bf16_f32 v103, v110, v111
	s_waitcnt lgkmcnt(6)
	v_mfma_f32_32x32x16_bf16 v[32:47], v[218:221], v[116:119], v[32:47]
	v_mfma_f32_32x32x16_bf16 v[0:15], v[218:221], v[84:87], v[0:15]
	ds_read_b64_tr_b16 v[234:235], v195 offset:16192
	ds_read_b64_tr_b16 v[236:237], v195 offset:17344
	v_pk_add_f32 v[244:245], v[244:245], v[64:65]
	v_pk_add_f32 v[244:245], v[244:245], v[66:67]
	v_pk_add_f32 v[244:245], v[244:245], v[68:69]
	v_cvt_pk_bf16_f32 v64, v64, v65
	v_pk_add_f32 v[244:245], v[244:245], v[70:71]
	v_cvt_pk_bf16_f32 v65, v66, v67
	v_pk_add_f32 v[244:245], v[244:245], v[72:73]
	v_cvt_pk_bf16_f32 v66, v68, v69
	v_pk_add_f32 v[244:245], v[244:245], v[74:75]
	v_cvt_pk_bf16_f32 v67, v70, v71
	v_pk_add_f32 v[244:245], v[244:245], v[76:77]
	v_cvt_pk_bf16_f32 v68, v72, v73
	v_pk_add_f32 v[244:245], v[244:245], v[78:79]
	v_cvt_pk_bf16_f32 v69, v74, v75
	v_cvt_pk_bf16_f32 v70, v76, v77
	v_cvt_pk_bf16_f32 v71, v78, v79
	s_waitcnt lgkmcnt(6)
	v_mfma_f32_32x32x16_bf16 v[48:63], v[222:225], v[96:99], v[48:63]
	v_mfma_f32_32x32x16_bf16 v[16:31], v[222:225], v[64:67], v[16:31]
	v_add_f32_e32 v238, v238, v239
	v_add_f32_e32 v244, v244, v245
	s_waitcnt lgkmcnt(4)
	v_mfma_f32_32x32x16_bf16 v[32:47], v[226:229], v[96:99], v[32:47]
	v_mfma_f32_32x32x16_bf16 v[0:15], v[226:229], v[64:67], v[0:15]
	v_add_f32_e32 v190, v190, v238
	v_add_f32_e32 v191, v191, v244
	s_waitcnt lgkmcnt(2)
	v_mfma_f32_32x32x16_bf16 v[48:63], v[230:233], v[100:103], v[48:63]
	v_mfma_f32_32x32x16_bf16 v[16:31], v[230:233], v[68:71], v[16:31]
	s_waitcnt lgkmcnt(0)
	v_mfma_f32_32x32x16_bf16 v[32:47], v[234:237], v[100:103], v[32:47]
	v_mfma_f32_32x32x16_bf16 v[0:15], v[234:237], v[68:71], v[0:15]
